# v24: instruction selection: conformer conv tap loop uses v_pk_fma_f32 on accumulator pairs (taps copied to two aligned banks), 64 VALU ops per pass instead of 124
# baseline (speedup 1.0000x reference)
; __device__ __forceinline__ void conv_unit_p(const bf16* __restrict__ Z, bf16* __restrict__ CAT, float* __restrict__ newc, ...
;     ...
;     float wk[31];
; #pragma unroll
;     for (int k = 0; k < 31; ++k) wk[k] = cw[k * GW + c];
;     ...
; #pragma unroll 1
;     for (int tq = 0; tq < 32; tq += 4) {
;         float acc[4] = {bias, bias, bias, bias};
; #pragma unroll
;         for (int r = 0; r < 34; ++r) { const float gvv = gL[(tq + r) * 64 + lane];
; #pragma unroll
;             for (int q = 0; q < 4; ++q) { const int k = r - q; if (k >= 0 && k <= 30) acc[q] += wk[k] * gvv; } }
.LBB0_409:
	s_or_b64 exec, exec, s[6:7]
	s_waitcnt lgkmcnt(0)
	s_nop 0
	v_lshl_add_u32 v0, v124, 2, s69
	s_mov_b32 s2, -4
	v_mov_b32_e32 v190, v87
	v_mov_b32_e32 v191, v88
	v_mov_b32_e32 v192, v89
	v_mov_b32_e32 v193, v90
	v_mov_b32_e32 v194, v95
	v_mov_b32_e32 v195, v91
	v_mov_b32_e32 v196, v92
	v_mov_b32_e32 v197, v93
	v_mov_b32_e32 v198, v96
	v_mov_b32_e32 v199, v97
	v_mov_b32_e32 v200, v98
	v_mov_b32_e32 v201, v99
	v_mov_b32_e32 v202, v100
	v_mov_b32_e32 v203, v94
	v_mov_b32_e32 v204, v110
	v_mov_b32_e32 v205, v111
	v_mov_b32_e32 v206, v101
	v_mov_b32_e32 v207, v102
	v_mov_b32_e32 v208, v103
	v_mov_b32_e32 v209, v104
	v_mov_b32_e32 v210, v105
	v_mov_b32_e32 v211, v112
	v_mov_b32_e32 v212, v113
	v_mov_b32_e32 v213, v114
	v_mov_b32_e32 v214, v106
	v_mov_b32_e32 v215, v107
	v_mov_b32_e32 v216, v108
	v_mov_b32_e32 v217, v109
	v_mov_b32_e32 v218, v115
	v_mov_b32_e32 v219, v116
	v_mov_b32_e32 v220, v117
	v_mov_b32_e32 v221, v87
	v_mov_b32_e32 v222, v88
	v_mov_b32_e32 v223, v89
	v_mov_b32_e32 v224, v90
	v_mov_b32_e32 v225, v95
	v_mov_b32_e32 v226, v91
	v_mov_b32_e32 v227, v92
	v_mov_b32_e32 v228, v93
	v_mov_b32_e32 v229, v96
	v_mov_b32_e32 v230, v97
	v_mov_b32_e32 v231, v98
	v_mov_b32_e32 v232, v99
	v_mov_b32_e32 v233, v100
	v_mov_b32_e32 v234, v94
	v_mov_b32_e32 v235, v110
	v_mov_b32_e32 v236, v111
	v_mov_b32_e32 v237, v101
	v_mov_b32_e32 v238, v102
	v_mov_b32_e32 v239, v103
	v_mov_b32_e32 v240, v104
	v_mov_b32_e32 v241, v105
	v_mov_b32_e32 v242, v112
	v_mov_b32_e32 v243, v113
	v_mov_b32_e32 v244, v114
	v_mov_b32_e32 v245, v106
	v_mov_b32_e32 v246, v107
	v_mov_b32_e32 v247, v108
	v_mov_b32_e32 v248, v109
	v_mov_b32_e32 v249, v115
	v_mov_b32_e32 v250, v116
	v_mov_b32_e32 v251, v117
.LBB0_410:
	ds_read2st64_b32 v[136:137], v0 offset1:1
	ds_read2st64_b32 v[138:139], v0 offset0:2 offset1:3
	ds_read2st64_b32 v[140:141], v0 offset0:4 offset1:5
	ds_read2st64_b32 v[142:143], v0 offset0:6 offset1:7
	ds_read2st64_b32 v[144:145], v0 offset0:8 offset1:9
	ds_read2st64_b32 v[146:147], v0 offset0:10 offset1:11
	ds_read2st64_b32 v[148:149], v0 offset0:12 offset1:13
	ds_read2st64_b32 v[150:151], v0 offset0:14 offset1:15
	ds_read2st64_b32 v[152:153], v0 offset0:16 offset1:17
	ds_read2st64_b32 v[154:155], v0 offset0:18 offset1:19
	ds_read2st64_b32 v[156:157], v0 offset0:20 offset1:21
	ds_read2st64_b32 v[158:159], v0 offset0:22 offset1:23
	s_add_i32 s2, s2, 4
	v_add_u32_e32 v4, 0x400, v0
	v_mov_b32_e32 v88, v118
	v_mov_b32_e32 v89, v118
	v_mov_b32_e32 v90, v118
	v_mov_b32_e32 v91, v118
	s_waitcnt lgkmcnt(11)
	v_fmac_f32_e32 v88, v190, v136
	v_pk_fma_f32 v[88:89], v[190:191], v[136:137], v[88:89] op_sel:[1,1,0] op_sel_hi:[0,1,1]
	ds_read2st64_b32 v[160:161], v0 offset0:24 offset1:25
	s_waitcnt lgkmcnt(11)
	v_pk_fma_f32 v[88:89], v[222:223], v[138:139], v[88:89] op_sel:[1,0,0] op_sel_hi:[0,0,1]
	v_fmac_f32_e32 v90, v190, v138
	v_pk_fma_f32 v[88:89], v[192:193], v[138:139], v[88:89] op_sel:[1,1,0] op_sel_hi:[0,1,1]
	v_pk_fma_f32 v[90:91], v[190:191], v[138:139], v[90:91] op_sel:[1,1,0] op_sel_hi:[0,1,1]
	ds_read2st64_b32 v[162:163], v0 offset0:26 offset1:27
	s_waitcnt lgkmcnt(11)
	v_pk_fma_f32 v[88:89], v[224:225], v[140:141], v[88:89] op_sel:[1,0,0] op_sel_hi:[0,0,1]
	v_pk_fma_f32 v[90:91], v[222:223], v[140:141], v[90:91] op_sel:[1,0,0] op_sel_hi:[0,0,1]
	v_pk_fma_f32 v[88:89], v[194:195], v[140:141], v[88:89] op_sel:[1,1,0] op_sel_hi:[0,1,1]
	v_pk_fma_f32 v[90:91], v[192:193], v[140:141], v[90:91] op_sel:[1,1,0] op_sel_hi:[0,1,1]
	ds_read2st64_b32 v[164:165], v0 offset0:28 offset1:29
	s_waitcnt lgkmcnt(11)
	v_pk_fma_f32 v[88:89], v[226:227], v[142:143], v[88:89] op_sel:[1,0,0] op_sel_hi:[0,0,1]
	v_pk_fma_f32 v[90:91], v[224:225], v[142:143], v[90:91] op_sel:[1,0,0] op_sel_hi:[0,0,1]
	v_pk_fma_f32 v[88:89], v[196:197], v[142:143], v[88:89] op_sel:[1,1,0] op_sel_hi:[0,1,1]
	v_pk_fma_f32 v[90:91], v[194:195], v[142:143], v[90:91] op_sel:[1,1,0] op_sel_hi:[0,1,1]
	ds_read2st64_b32 v[166:167], v0 offset0:30 offset1:31
	s_waitcnt lgkmcnt(11)
	v_pk_fma_f32 v[88:89], v[228:229], v[144:145], v[88:89] op_sel:[1,0,0] op_sel_hi:[0,0,1]
	v_pk_fma_f32 v[90:91], v[226:227], v[144:145], v[90:91] op_sel:[1,0,0] op_sel_hi:[0,0,1]
	v_pk_fma_f32 v[88:89], v[198:199], v[144:145], v[88:89] op_sel:[1,1,0] op_sel_hi:[0,1,1]
	v_pk_fma_f32 v[90:91], v[196:197], v[144:145], v[90:91] op_sel:[1,1,0] op_sel_hi:[0,1,1]
	ds_read2st64_b32 v[188:189], v0 offset0:32 offset1:33
	s_waitcnt lgkmcnt(11)
	v_pk_fma_f32 v[88:89], v[230:231], v[146:147], v[88:89] op_sel:[1,0,0] op_sel_hi:[0,0,1]
	v_pk_fma_f32 v[90:91], v[228:229], v[146:147], v[90:91] op_sel:[1,0,0] op_sel_hi:[0,0,1]
	v_pk_fma_f32 v[88:89], v[200:201], v[146:147], v[88:89] op_sel:[1,1,0] op_sel_hi:[0,1,1]
	v_pk_fma_f32 v[90:91], v[198:199], v[146:147], v[90:91] op_sel:[1,1,0] op_sel_hi:[0,1,1]
	s_waitcnt lgkmcnt(10)
	v_pk_fma_f32 v[88:89], v[232:233], v[148:149], v[88:89] op_sel:[1,0,0] op_sel_hi:[0,0,1]
	v_pk_fma_f32 v[90:91], v[230:231], v[148:149], v[90:91] op_sel:[1,0,0] op_sel_hi:[0,0,1]
	v_pk_fma_f32 v[88:89], v[202:203], v[148:149], v[88:89] op_sel:[1,1,0] op_sel_hi:[0,1,1]
	v_pk_fma_f32 v[90:91], v[200:201], v[148:149], v[90:91] op_sel:[1,1,0] op_sel_hi:[0,1,1]
	s_waitcnt lgkmcnt(9)
	v_pk_fma_f32 v[88:89], v[234:235], v[150:151], v[88:89] op_sel:[1,0,0] op_sel_hi:[0,0,1]
	v_pk_fma_f32 v[90:91], v[232:233], v[150:151], v[90:91] op_sel:[1,0,0] op_sel_hi:[0,0,1]
	v_pk_fma_f32 v[88:89], v[204:205], v[150:151], v[88:89] op_sel:[1,1,0] op_sel_hi:[0,1,1]
	v_pk_fma_f32 v[90:91], v[202:203], v[150:151], v[90:91] op_sel:[1,1,0] op_sel_hi:[0,1,1]
	s_waitcnt lgkmcnt(8)
; #define LDS_WAIT() asm volatile("s_waitcnt lgkmcnt(0)" ::: "memory")
; __device__ __forceinline__ void conv_unit_p(const bf16* __restrict__ Z, bf16* __restrict__ CAT, float* __restrict__ newc, ...
;     ...
;         for (int r = 0; r < 34; ++r) { const float gvv = gL[(tq + r) * 64 + lane];
; #pragma unroll
;             for (int q = 0; q < 4; ++q) { const int k = r - q; if (k >= 0 && k <= 30) acc[q] += wk[k] * gvv; } }
;         LDS_WAIT();
; #pragma unroll
;         for (int q = 0; q < 4; ++q) gL[(tq + q) * 64 + lane] = acc[q];
;     }
	v_pk_fma_f32 v[88:89], v[236:237], v[152:153], v[88:89] op_sel:[1,0,0] op_sel_hi:[0,0,1]
	v_pk_fma_f32 v[90:91], v[234:235], v[152:153], v[90:91] op_sel:[1,0,0] op_sel_hi:[0,0,1]
	v_pk_fma_f32 v[88:89], v[206:207], v[152:153], v[88:89] op_sel:[1,1,0] op_sel_hi:[0,1,1]
	v_pk_fma_f32 v[90:91], v[204:205], v[152:153], v[90:91] op_sel:[1,1,0] op_sel_hi:[0,1,1]
	s_waitcnt lgkmcnt(7)
	v_pk_fma_f32 v[88:89], v[238:239], v[154:155], v[88:89] op_sel:[1,0,0] op_sel_hi:[0,0,1]
	v_pk_fma_f32 v[90:91], v[236:237], v[154:155], v[90:91] op_sel:[1,0,0] op_sel_hi:[0,0,1]
	v_pk_fma_f32 v[88:89], v[208:209], v[154:155], v[88:89] op_sel:[1,1,0] op_sel_hi:[0,1,1]
	v_pk_fma_f32 v[90:91], v[206:207], v[154:155], v[90:91] op_sel:[1,1,0] op_sel_hi:[0,1,1]
	s_waitcnt lgkmcnt(6)
	v_pk_fma_f32 v[88:89], v[240:241], v[156:157], v[88:89] op_sel:[1,0,0] op_sel_hi:[0,0,1]
	v_pk_fma_f32 v[90:91], v[238:239], v[156:157], v[90:91] op_sel:[1,0,0] op_sel_hi:[0,0,1]
	v_pk_fma_f32 v[88:89], v[210:211], v[156:157], v[88:89] op_sel:[1,1,0] op_sel_hi:[0,1,1]
	v_pk_fma_f32 v[90:91], v[208:209], v[156:157], v[90:91] op_sel:[1,1,0] op_sel_hi:[0,1,1]
	s_waitcnt lgkmcnt(5)
	v_pk_fma_f32 v[88:89], v[242:243], v[158:159], v[88:89] op_sel:[1,0,0] op_sel_hi:[0,0,1]
	v_pk_fma_f32 v[90:91], v[240:241], v[158:159], v[90:91] op_sel:[1,0,0] op_sel_hi:[0,0,1]
	v_pk_fma_f32 v[88:89], v[212:213], v[158:159], v[88:89] op_sel:[1,1,0] op_sel_hi:[0,1,1]
	v_pk_fma_f32 v[90:91], v[210:211], v[158:159], v[90:91] op_sel:[1,1,0] op_sel_hi:[0,1,1]
	s_waitcnt lgkmcnt(4)
	v_pk_fma_f32 v[88:89], v[244:245], v[160:161], v[88:89] op_sel:[1,0,0] op_sel_hi:[0,0,1]
	v_pk_fma_f32 v[90:91], v[242:243], v[160:161], v[90:91] op_sel:[1,0,0] op_sel_hi:[0,0,1]
	v_pk_fma_f32 v[88:89], v[214:215], v[160:161], v[88:89] op_sel:[1,1,0] op_sel_hi:[0,1,1]
	v_pk_fma_f32 v[90:91], v[212:213], v[160:161], v[90:91] op_sel:[1,1,0] op_sel_hi:[0,1,1]
	s_waitcnt lgkmcnt(3)
	v_pk_fma_f32 v[88:89], v[246:247], v[162:163], v[88:89] op_sel:[1,0,0] op_sel_hi:[0,0,1]
	v_pk_fma_f32 v[90:91], v[244:245], v[162:163], v[90:91] op_sel:[1,0,0] op_sel_hi:[0,0,1]
	v_pk_fma_f32 v[88:89], v[216:217], v[162:163], v[88:89] op_sel:[1,1,0] op_sel_hi:[0,1,1]
	v_pk_fma_f32 v[90:91], v[214:215], v[162:163], v[90:91] op_sel:[1,1,0] op_sel_hi:[0,1,1]
	s_waitcnt lgkmcnt(2)
	v_pk_fma_f32 v[88:89], v[248:249], v[164:165], v[88:89] op_sel:[1,0,0] op_sel_hi:[0,0,1]
	v_pk_fma_f32 v[90:91], v[246:247], v[164:165], v[90:91] op_sel:[1,0,0] op_sel_hi:[0,0,1]
	v_pk_fma_f32 v[88:89], v[218:219], v[164:165], v[88:89] op_sel:[1,1,0] op_sel_hi:[0,1,1]
	v_pk_fma_f32 v[90:91], v[216:217], v[164:165], v[90:91] op_sel:[1,1,0] op_sel_hi:[0,1,1]
	s_waitcnt lgkmcnt(1)
	v_pk_fma_f32 v[88:89], v[250:251], v[166:167], v[88:89] op_sel:[1,0,0] op_sel_hi:[0,0,1]
	v_pk_fma_f32 v[90:91], v[248:249], v[166:167], v[90:91] op_sel:[1,0,0] op_sel_hi:[0,0,1]
	v_fmac_f32_e32 v89, v220, v167
	v_pk_fma_f32 v[90:91], v[218:219], v[166:167], v[90:91] op_sel:[1,1,0] op_sel_hi:[0,1,1]
	s_waitcnt lgkmcnt(0)
	v_pk_fma_f32 v[90:91], v[250:251], v[188:189], v[90:91] op_sel:[1,0,0] op_sel_hi:[0,0,1]
	v_fmac_f32_e32 v91, v220, v189
	s_cmp_lt_u32 s2, 28
	s_waitcnt lgkmcnt(0)
	ds_write2st64_b32 v0, v88, v89 offset1:1
	ds_write2st64_b32 v0, v90, v91 offset0:2 offset1:3
	v_mov_b32_e32 v0, v4
	s_cbranch_scc1 .LBB0_410
	v_mov_b64_e32 v[0:1], s[70:71]
	s_waitcnt lgkmcnt(0)
	v_mad_u64_u32 v[16:17], s[6:7], s84, v181, v[0:1]
	global_load_dwordx4 v[4:7], v128, s[54:55] offset:16
	global_load_dwordx4 v[12:15], v128, s[54:55]
	global_load_dwordx4 v[0:3], v128, s[26:27] offset:16
	global_load_dwordx4 v[8:11], v128, s[26:27]
	ds_read_b128 v[18:21], v67
	ds_read_b128 v[22:25], v67 offset:16
	s_or_b32 s4, s4, s74
	s_lshl_b64 s[4:5], s[4:5], 11
	v_lshl_add_u64 v[16:17], v[16:17], 0, s[4:5]
	s_waitcnt lgkmcnt(1)
	v_mov_b32_e32 v26, v18
	s_waitcnt lgkmcnt(0)
	v_mov_b32_e32 v27, v22
	v_mov_b32_e32 v28, v19
	v_mov_b32_e32 v29, v23
	v_pk_add_f32 v[26:27], v[26:27], v[28:29]
	v_mov_b32_e32 v28, v20
	v_mov_b32_e32 v29, v24
	v_mov_b32_e32 v30, v21
	v_mov_b32_e32 v31, v25
	v_pk_add_f32 v[28:29], v[28:29], v[30:31]
	v_mov_b32_e32 v65, v129
	v_pk_add_f32 v[26:27], v[26:27], v[28:29]
	v_lshl_add_u64 v[16:17], v[16:17], 0, v[64:65]
	v_add_f32_e32 v26, v26, v27
	s_mov_b64 s[4:5], 0x900200
	v_lshl_add_u64 v[16:17], v[16:17], 0, s[4:5]
	v_add_f32_dpp v26, v26, v26 quad_perm:[1,0,3,2] row_mask:0xf bank_mask:0xf bound_ctrl:1
	s_mov_b32 s2, 36
	v_readlane_b32 s70, v254, 58
	v_add_f32_dpp v26, v26, v26 quad_perm:[2,3,0,1] row_mask:0xf bank_mask:0xf bound_ctrl:1
	s_nop 1
	v_add_f32_dpp v26, v26, v26 row_half_mirror row_mask:0xf bank_mask:0xf bound_ctrl:1
	v_mul_f32_e32 v26, 0x3c800000, v26
	v_pk_add_f32 v[28:29], v[18:19], v[26:27] op_sel_hi:[1,0] neg_lo:[0,1] neg_hi:[0,1]
	v_pk_add_f32 v[20:21], v[20:21], v[26:27] op_sel_hi:[1,0] neg_lo:[0,1] neg_hi:[0,1]
	v_pk_mul_f32 v[30:31], v[28:29], v[28:29]
	v_pk_mul_f32 v[32:33], v[20:21], v[20:21]
	v_pk_add_f32 v[22:23], v[22:23], v[26:27] op_sel_hi:[1,0] neg_lo:[0,1] neg_hi:[0,1]
	v_pk_add_f32 v[18:19], v[24:25], v[26:27] op_sel_hi:[1,0] neg_lo:[0,1] neg_hi:[0,1]
	v_add_f32_e32 v26, v30, v31
	v_add_f32_e32 v26, v32, v26
	v_pk_mul_f32 v[34:35], v[22:23], v[22:23]
	v_add_f32_e32 v26, v33, v26
	v_add_f32_e32 v26, v34, v26
	v_pk_mul_f32 v[24:25], v[18:19], v[18:19]
	v_add_f32_e32 v26, v35, v26
	v_add_f32_e32 v24, v24, v26
	v_add_f32_e32 v24, v25, v24
	s_nop 1
	v_add_f32_dpp v24, v24, v24 quad_perm:[1,0,3,2] row_mask:0xf bank_mask:0xf bound_ctrl:1
	s_nop 1
	v_add_f32_dpp v24, v24, v24 quad_perm:[2,3,0,1] row_mask:0xf bank_mask:0xf bound_ctrl:1
	s_nop 1
	v_add_f32_dpp v24, v24, v24 row_half_mirror row_mask:0xf bank_mask:0xf bound_ctrl:1
	v_fmamk_f32 v24, v24, 0x3c800000, v168
	v_cmp_gt_f32_e32 vcc, s79, v24
	v_mul_f32_e32 v25, 0x4b800000, v24
	s_nop 0
	v_cndmask_b32_e32 v24, v24, v25, vcc
	v_rsq_f32_e32 v24, v24
	s_nop 0
	v_mul_f32_e32 v25, 0x45800000, v24
	v_cndmask_b32_e32 v24, v24, v25, vcc
	v_mul_f32_e32 v25, v28, v24
	v_mul_f32_e32 v20, v20, v24
	v_mul_f32_e32 v21, v21, v24
	v_mul_f32_e32 v22, v22, v24
	v_mul_f32_e32 v23, v23, v24
	v_mul_f32_e32 v18, v18, v24
	s_waitcnt vmcnt(1)
; #define LAS __attribute__((address_space(3)))
; __device__ __forceinline__ float sum8(float v) { v += dpp_get<0xB1, 0xF>(v); v += dpp_get<0x4E, 0xF>(v); v += dpp_get<0x141, 0xF>(v); return v; }
; __device__ __forceinline__ v4u pack8(const float (&f)[8]) { v4u w; w.x = pg8::cvt_pk_bf16(f[0], f[1]); w.y = pg8::cvt_pk_bf16(f[2], f[3]); w.z = pg8::cvt_pk_bf16(f[4], f[5]); w.w = pg8::cvt_pk_bf16(f[6], f[7]); return w; }
; __device__ __forceinline__ float sigm(float x) { return __builtin_amdgcn_rcpf(1.f + __builtin_amdgcn_exp2f(-1.44269504f * x)); }
; __device__ __forceinline__ void conv_unit_p(const bf16* __restrict__ Z, bf16* __restrict__ CAT, float* __restrict__ newc, ...
;     ...
;     for (int j = 0; j < 4; ++j) { const int r = 8 * j + rr; const f32x4 a = *(const LAS f32x4*)(gL + r * 64 + cg * 8), b = *(const LAS f32x4*)(gL + r * 64 + cg * 8 + 4);
;         float x[8] = {a[0], a[1], a[2], a[3], b[0], b[1], b[2], b[3]};
;         const float mean = sum8(((x[0] + x[1]) + (x[2] + x[3])) + ((x[4] + x[5]) + (x[6] + x[7]))) * (1.f / 64.f);
;         float q = 0.f;
; #pragma unroll
;         for (int i = 0; i < 8; ++i) { x[i] -= mean; q += x[i] * x[i]; }
;         const float rstd = rsqrtf(sum8(q) * (1.f / 64.f) + EPS);
; #pragma unroll
;         for (int i = 0; i < 8; ++i) { const float yy = x[i] * rstd * gg[i] + bb[i]; x[i] = yy * sigm(yy); }
;         *(v4u*)(ob + r * DP) = pack8(x); }
	v_fma_f32 v22, v4, v22, v0
	s_waitcnt vmcnt(0)
	v_fma_f32 v25, v12, v25, v8
	v_mul_f32_e32 v26, 0xbfb8aa3b, v25
	v_exp_f32_e32 v26, v26
	v_fma_f32 v20, v14, v20, v10
	v_fma_f32 v21, v15, v21, v11
	v_fma_f32 v23, v5, v23, v1
	v_add_f32_e32 v26, 1.0, v26
	v_rcp_f32_e32 v26, v26
	v_fma_f32 v18, v6, v18, v2
	v_mul_f32_e32 v25, v25, v26
	v_mul_f32_e32 v26, v29, v24
	v_fma_f32 v26, v13, v26, v9
	v_mul_f32_e32 v27, 0xbfb8aa3b, v26
	v_exp_f32_e32 v27, v27
	s_nop 0
	v_add_f32_e32 v27, 1.0, v27
	v_rcp_f32_e32 v27, v27
	s_nop 0
	v_mul_f32_e32 v26, v26, v27
	v_mul_f32_e32 v27, 0xbfb8aa3b, v20
	v_exp_f32_e32 v27, v27
	s_nop 0
	v_add_f32_e32 v27, 1.0, v27
	v_rcp_f32_e32 v27, v27
	s_nop 0
	v_mul_f32_e32 v20, v20, v27
	v_mul_f32_e32 v27, 0xbfb8aa3b, v21
	v_exp_f32_e32 v27, v27
	s_nop 0
	v_add_f32_e32 v27, 1.0, v27
	v_rcp_f32_e32 v27, v27
	s_nop 0
	v_mul_f32_e32 v21, v21, v27
	v_mul_f32_e32 v27, 0xbfb8aa3b, v22
	v_exp_f32_e32 v27, v27
	s_nop 0
	v_add_f32_e32 v27, 1.0, v27
	v_rcp_f32_e32 v27, v27
	s_nop 0
	v_mul_f32_e32 v22, v22, v27
	v_mul_f32_e32 v27, 0xbfb8aa3b, v23
	v_exp_f32_e32 v27, v27
	s_nop 0
	v_add_f32_e32 v27, 1.0, v27
	v_rcp_f32_e32 v27, v27
	s_nop 0
	v_mul_f32_e32 v23, v23, v27
	v_mul_f32_e32 v27, 0xbfb8aa3b, v18
	v_exp_f32_e32 v27, v27
	s_nop 0
	v_add_f32_e32 v27, 1.0, v27
	v_rcp_f32_e32 v27, v27
	s_nop 0
	v_mul_f32_e32 v27, v18, v27
	v_mul_f32_e32 v18, v19, v24
	v_fma_f32 v18, v7, v18, v3
	v_mul_f32_e32 v19, 0xbfb8aa3b, v18
	v_exp_f32_e32 v19, v19
	s_nop 0
	v_add_f32_e32 v19, 1.0, v19
	v_rcp_f32_e32 v19, v19
	s_nop 0
	v_mul_f32_e32 v24, v18, v19
	v_cvt_pk_bf16_f32 v18, v25, v26
	v_cvt_pk_bf16_f32 v19, v20, v21
	v_cvt_pk_bf16_f32 v20, v22, v23
	v_lshlrev_b32_e32 v22, 10, v86
	v_ashrrev_i32_e32 v23, 31, v22
	v_lshl_add_u64 v[22:23], v[22:23], 1, v[16:17]
	v_cvt_pk_bf16_f32 v21, v27, v24
	global_store_dwordx4 v[22:23], v[18:21], off
	ds_read_b128 v[18:21], v56
	ds_read_b128 v[22:25], v56 offset:16
	s_waitcnt lgkmcnt(1)
	v_mov_b32_e32 v26, v18
	s_waitcnt lgkmcnt(0)
	v_mov_b32_e32 v27, v22
	v_mov_b32_e32 v28, v19
	v_mov_b32_e32 v29, v23
	v_pk_add_f32 v[26:27], v[26:27], v[28:29]
	v_mov_b32_e32 v28, v20
	v_mov_b32_e32 v29, v24
	v_mov_b32_e32 v30, v21
	v_mov_b32_e32 v31, v25
	v_pk_add_f32 v[28:29], v[28:29], v[30:31]
	s_nop 0
	v_pk_add_f32 v[26:27], v[26:27], v[28:29]
	s_nop 0
	v_add_f32_e32 v26, v26, v27
	s_nop 1
	v_add_f32_dpp v26, v26, v26 quad_perm:[1,0,3,2] row_mask:0xf bank_mask:0xf bound_ctrl:1
	s_nop 1
	v_add_f32_dpp v26, v26, v26 quad_perm:[2,3,0,1] row_mask:0xf bank_mask:0xf bound_ctrl:1
	s_nop 1
	v_add_f32_dpp v26, v26, v26 row_half_mirror row_mask:0xf bank_mask:0xf bound_ctrl:1
	v_mul_f32_e32 v26, 0x3c800000, v26
	v_pk_add_f32 v[18:19], v[18:19], v[26:27] op_sel_hi:[1,0] neg_lo:[0,1] neg_hi:[0,1]
	v_pk_add_f32 v[20:21], v[20:21], v[26:27] op_sel_hi:[1,0] neg_lo:[0,1] neg_hi:[0,1]
	v_pk_mul_f32 v[28:29], v[18:19], v[18:19]
	v_pk_mul_f32 v[30:31], v[20:21], v[20:21]
	v_add_f32_e32 v28, v28, v29
	v_pk_add_f32 v[22:23], v[22:23], v[26:27] op_sel_hi:[1,0] neg_lo:[0,1] neg_hi:[0,1]
	v_add_f32_e32 v28, v30, v28
	v_pk_mul_f32 v[32:33], v[22:23], v[22:23]
	v_add_f32_e32 v28, v31, v28
	v_pk_add_f32 v[24:25], v[24:25], v[26:27] op_sel_hi:[1,0] neg_lo:[0,1] neg_hi:[0,1]
	v_add_f32_e32 v28, v32, v28
	v_pk_mul_f32 v[26:27], v[24:25], v[24:25]
	v_add_f32_e32 v28, v33, v28
	v_add_f32_e32 v26, v26, v28
	v_add_f32_e32 v26, v27, v26
	s_nop 1
	v_add_f32_dpp v26, v26, v26 quad_perm:[1,0,3,2] row_mask:0xf bank_mask:0xf bound_ctrl:1
	s_nop 1
	v_add_f32_dpp v26, v26, v26 quad_perm:[2,3,0,1] row_mask:0xf bank_mask:0xf bound_ctrl:1
	s_nop 1
	v_add_f32_dpp v26, v26, v26 row_half_mirror row_mask:0xf bank_mask:0xf bound_ctrl:1
	v_fmamk_f32 v26, v26, 0x3c800000, v168
	v_cmp_gt_f32_e32 vcc, s79, v26
	v_mul_f32_e32 v27, 0x4b800000, v26
	s_nop 0
	v_cndmask_b32_e32 v26, v26, v27, vcc
	v_rsq_f32_e32 v26, v26
	s_nop 0
	v_mul_f32_e32 v27, 0x45800000, v26
	v_cndmask_b32_e32 v26, v26, v27, vcc
	v_mul_f32_e32 v18, v18, v26
	v_fma_f32 v18, v12, v18, v8
	v_mul_f32_e32 v27, 0xbfb8aa3b, v18
	v_exp_f32_e32 v27, v27
	v_mul_f32_e32 v19, v19, v26
	v_fma_f32 v19, v13, v19, v9
	v_mul_f32_e32 v20, v20, v26
	v_add_f32_e32 v27, 1.0, v27
	v_rcp_f32_e32 v27, v27
	v_fma_f32 v20, v14, v20, v10
	v_mul_f32_e32 v21, v21, v26
	v_fma_f32 v21, v15, v21, v11
	v_mul_f32_e32 v18, v18, v27
	v_mul_f32_e32 v27, 0xbfb8aa3b, v19
	v_exp_f32_e32 v27, v27
	v_mul_f32_e32 v22, v22, v26
	v_fma_f32 v22, v4, v22, v0
	v_mul_f32_e32 v23, v23, v26
	v_add_f32_e32 v27, 1.0, v27
	v_rcp_f32_e32 v27, v27
	v_fma_f32 v23, v5, v23, v1
	v_mul_f32_e32 v24, v24, v26
	v_mul_f32_e32 v25, v25, v26
	v_mul_f32_e32 v19, v19, v27
	v_mul_f32_e32 v27, 0xbfb8aa3b, v20
	v_exp_f32_e32 v27, v27
	v_fma_f32 v24, v6, v24, v2
	v_fma_f32 v25, v7, v25, v3
	v_mul_f32_e32 v26, 0xbfb8aa3b, v25
	v_add_f32_e32 v27, 1.0, v27
	v_rcp_f32_e32 v27, v27
	v_exp_f32_e32 v26, v26
	v_cvt_pk_bf16_f32 v18, v18, v19
	v_mul_f32_e32 v20, v20, v27
	v_mul_f32_e32 v27, 0xbfb8aa3b, v21
	v_exp_f32_e32 v27, v27
	v_add_f32_e32 v26, 1.0, v26
	v_rcp_f32_e32 v26, v26
	v_add_f32_e32 v27, 1.0, v27
	v_rcp_f32_e32 v27, v27
	v_mul_f32_e32 v25, v25, v26
	v_mul_f32_e32 v21, v21, v27
	v_mul_f32_e32 v27, 0xbfb8aa3b, v22
	v_exp_f32_e32 v27, v27
	v_cvt_pk_bf16_f32 v19, v20, v21
	s_nop 0
	v_add_f32_e32 v27, 1.0, v27
	v_rcp_f32_e32 v27, v27
	s_nop 0
	v_mul_f32_e32 v22, v22, v27
	v_mul_f32_e32 v27, 0xbfb8aa3b, v23
	v_exp_f32_e32 v27, v27
	s_nop 0
	v_add_f32_e32 v27, 1.0, v27
	v_rcp_f32_e32 v27, v27
	s_nop 0
	v_mul_f32_e32 v23, v23, v27
	v_mul_f32_e32 v27, 0xbfb8aa3b, v24
	v_exp_f32_e32 v27, v27
	v_cvt_pk_bf16_f32 v20, v22, v23
	v_lshlrev_b32_e32 v22, 10, v85
	v_ashrrev_i32_e32 v23, 31, v22
	v_add_f32_e32 v27, 1.0, v27
	v_rcp_f32_e32 v27, v27
	v_lshl_add_u64 v[22:23], v[22:23], 1, v[16:17]
	v_mul_f32_e32 v24, v24, v27
	v_cvt_pk_bf16_f32 v21, v24, v25
	global_store_dwordx4 v[22:23], v[18:21], off
	ds_read_b128 v[18:21], v48
	ds_read_b128 v[22:25], v48 offset:16
	s_waitcnt lgkmcnt(1)
; #define LAS __attribute__((address_space(3)))
; __device__ __forceinline__ float sum8(float v) { v += dpp_get<0xB1, 0xF>(v); v += dpp_get<0x4E, 0xF>(v); v += dpp_get<0x141, 0xF>(v); return v; }
; __device__ __forceinline__ v4u pack8(const float (&f)[8]) { v4u w; w.x = pg8::cvt_pk_bf16(f[0], f[1]); w.y = pg8::cvt_pk_bf16(f[2], f[3]); w.z = pg8::cvt_pk_bf16(f[4], f[5]); w.w = pg8::cvt_pk_bf16(f[6], f[7]); return w; }
; __device__ __forceinline__ float sigm(float x) { return __builtin_amdgcn_rcpf(1.f + __builtin_amdgcn_exp2f(-1.44269504f * x)); }
; __device__ __forceinline__ void conv_unit_p(const bf16* __restrict__ Z, bf16* __restrict__ CAT, float* __restrict__ newc, ...
;     ...
;     for (int j = 0; j < 4; ++j) { const int r = 8 * j + rr; const f32x4 a = *(const LAS f32x4*)(gL + r * 64 + cg * 8), b = *(const LAS f32x4*)(gL + r * 64 + cg * 8 + 4);
;         float x[8] = {a[0], a[1], a[2], a[3], b[0], b[1], b[2], b[3]};
;         const float mean = sum8(((x[0] + x[1]) + (x[2] + x[3])) + ((x[4] + x[5]) + (x[6] + x[7]))) * (1.f / 64.f);
;         float q = 0.f;
; #pragma unroll
;         for (int i = 0; i < 8; ++i) { x[i] -= mean; q += x[i] * x[i]; }
;         const float rstd = rsqrtf(sum8(q) * (1.f / 64.f) + EPS);
; #pragma unroll
;         for (int i = 0; i < 8; ++i) { const float yy = x[i] * rstd * gg[i] + bb[i]; x[i] = yy * sigm(yy); }
;         *(v4u*)(ob + r * DP) = pack8(x); }
	v_mov_b32_e32 v26, v18
	s_waitcnt lgkmcnt(0)
	v_mov_b32_e32 v27, v22
	v_mov_b32_e32 v28, v19
	v_mov_b32_e32 v29, v23
	v_pk_add_f32 v[26:27], v[26:27], v[28:29]
	v_mov_b32_e32 v28, v20
	v_mov_b32_e32 v29, v24
	v_mov_b32_e32 v30, v21
	v_mov_b32_e32 v31, v25
	v_pk_add_f32 v[28:29], v[28:29], v[30:31]
	s_nop 0
	v_pk_add_f32 v[26:27], v[26:27], v[28:29]
	s_nop 0
	v_add_f32_e32 v26, v26, v27
	s_nop 1
	v_add_f32_dpp v26, v26, v26 quad_perm:[1,0,3,2] row_mask:0xf bank_mask:0xf bound_ctrl:1
	s_nop 1
	v_add_f32_dpp v26, v26, v26 quad_perm:[2,3,0,1] row_mask:0xf bank_mask:0xf bound_ctrl:1
	s_nop 1
	v_add_f32_dpp v26, v26, v26 row_half_mirror row_mask:0xf bank_mask:0xf bound_ctrl:1
	v_mul_f32_e32 v26, 0x3c800000, v26
	v_pk_add_f32 v[18:19], v[18:19], v[26:27] op_sel_hi:[1,0] neg_lo:[0,1] neg_hi:[0,1]
	v_pk_add_f32 v[20:21], v[20:21], v[26:27] op_sel_hi:[1,0] neg_lo:[0,1] neg_hi:[0,1]
	v_pk_mul_f32 v[28:29], v[18:19], v[18:19]
	v_pk_mul_f32 v[30:31], v[20:21], v[20:21]
	v_add_f32_e32 v28, v28, v29
	v_pk_add_f32 v[22:23], v[22:23], v[26:27] op_sel_hi:[1,0] neg_lo:[0,1] neg_hi:[0,1]
	v_add_f32_e32 v28, v30, v28
	v_pk_mul_f32 v[32:33], v[22:23], v[22:23]
	v_add_f32_e32 v28, v31, v28
	v_pk_add_f32 v[24:25], v[24:25], v[26:27] op_sel_hi:[1,0] neg_lo:[0,1] neg_hi:[0,1]
	v_add_f32_e32 v28, v32, v28
	v_pk_mul_f32 v[26:27], v[24:25], v[24:25]
	v_add_f32_e32 v28, v33, v28
	v_add_f32_e32 v26, v26, v28
	v_add_f32_e32 v26, v27, v26
	s_nop 1
	v_add_f32_dpp v26, v26, v26 quad_perm:[1,0,3,2] row_mask:0xf bank_mask:0xf bound_ctrl:1
	s_nop 1
	v_add_f32_dpp v26, v26, v26 quad_perm:[2,3,0,1] row_mask:0xf bank_mask:0xf bound_ctrl:1
	s_nop 1
	v_add_f32_dpp v26, v26, v26 row_half_mirror row_mask:0xf bank_mask:0xf bound_ctrl:1
	v_fmamk_f32 v26, v26, 0x3c800000, v168
	v_cmp_gt_f32_e32 vcc, s79, v26
	v_mul_f32_e32 v27, 0x4b800000, v26
	s_nop 0
	v_cndmask_b32_e32 v26, v26, v27, vcc
	v_rsq_f32_e32 v26, v26
	s_nop 0
	v_mul_f32_e32 v27, 0x45800000, v26
	v_cndmask_b32_e32 v26, v26, v27, vcc
	v_mul_f32_e32 v18, v18, v26
	v_fma_f32 v18, v12, v18, v8
	v_mul_f32_e32 v27, 0xbfb8aa3b, v18
	v_exp_f32_e32 v27, v27
	v_mul_f32_e32 v19, v19, v26
	v_fma_f32 v19, v13, v19, v9
	v_mul_f32_e32 v20, v20, v26
	v_add_f32_e32 v27, 1.0, v27
	v_rcp_f32_e32 v27, v27
	v_fma_f32 v20, v14, v20, v10
	v_mul_f32_e32 v21, v21, v26
	v_fma_f32 v21, v15, v21, v11
	v_mul_f32_e32 v18, v18, v27
	v_mul_f32_e32 v27, 0xbfb8aa3b, v19
	v_exp_f32_e32 v27, v27
	v_mul_f32_e32 v22, v22, v26
	v_fma_f32 v22, v4, v22, v0
	v_mul_f32_e32 v23, v23, v26
	v_add_f32_e32 v27, 1.0, v27
	v_rcp_f32_e32 v27, v27
	v_fma_f32 v23, v5, v23, v1
	v_mul_f32_e32 v24, v24, v26
	v_mul_f32_e32 v25, v25, v26
	v_mul_f32_e32 v19, v19, v27
	v_mul_f32_e32 v27, 0xbfb8aa3b, v20
	v_exp_f32_e32 v27, v27
	v_fma_f32 v24, v6, v24, v2
	v_fma_f32 v25, v7, v25, v3
	v_mul_f32_e32 v26, 0xbfb8aa3b, v25
	v_add_f32_e32 v27, 1.0, v27
	v_rcp_f32_e32 v27, v27
	v_exp_f32_e32 v26, v26
	v_cvt_pk_bf16_f32 v18, v18, v19
	v_mul_f32_e32 v20, v20, v27
	v_mul_f32_e32 v27, 0xbfb8aa3b, v21
	v_exp_f32_e32 v27, v27
	v_add_f32_e32 v26, 1.0, v26
	v_rcp_f32_e32 v26, v26
	v_add_f32_e32 v27, 1.0, v27
	v_rcp_f32_e32 v27, v27
	v_mul_f32_e32 v25, v25, v26
	v_mul_f32_e32 v21, v21, v27
	v_mul_f32_e32 v27, 0xbfb8aa3b, v22
	v_exp_f32_e32 v27, v27
	v_cvt_pk_bf16_f32 v19, v20, v21
	s_nop 0
	v_add_f32_e32 v27, 1.0, v27
	v_rcp_f32_e32 v27, v27
	s_nop 0
	v_mul_f32_e32 v22, v22, v27
	v_mul_f32_e32 v27, 0xbfb8aa3b, v23
	v_exp_f32_e32 v27, v27
	s_nop 0
	v_add_f32_e32 v27, 1.0, v27
	v_rcp_f32_e32 v27, v27
	s_nop 0
	v_mul_f32_e32 v23, v23, v27
	v_mul_f32_e32 v27, 0xbfb8aa3b, v24
	v_exp_f32_e32 v27, v27
	v_cvt_pk_bf16_f32 v20, v22, v23
	v_lshlrev_b32_e32 v22, 10, v83
	v_ashrrev_i32_e32 v23, 31, v22
	v_add_f32_e32 v27, 1.0, v27
	v_rcp_f32_e32 v27, v27
	v_lshl_add_u64 v[22:23], v[22:23], 1, v[16:17]
	v_mul_f32_e32 v24, v24, v27
	v_cvt_pk_bf16_f32 v21, v24, v25
	global_store_dwordx4 v[22:23], v[18:21], off
	ds_read_b128 v[18:21], v40
	ds_read_b128 v[22:25], v40 offset:16
	s_waitcnt lgkmcnt(1)
; #define LAS __attribute__((address_space(3)))
; __device__ __forceinline__ float sum8(float v) { v += dpp_get<0xB1, 0xF>(v); v += dpp_get<0x4E, 0xF>(v); v += dpp_get<0x141, 0xF>(v); return v; }
; __device__ __forceinline__ v4u pack8(const float (&f)[8]) { v4u w; w.x = pg8::cvt_pk_bf16(f[0], f[1]); w.y = pg8::cvt_pk_bf16(f[2], f[3]); w.z = pg8::cvt_pk_bf16(f[4], f[5]); w.w = pg8::cvt_pk_bf16(f[6], f[7]); return w; }
; __device__ __forceinline__ float sigm(float x) { return __builtin_amdgcn_rcpf(1.f + __builtin_amdgcn_exp2f(-1.44269504f * x)); }
; __device__ __forceinline__ void conv_unit_p(const bf16* __restrict__ Z, bf16* __restrict__ CAT, float* __restrict__ newc, ...
;     ...
; #pragma unroll
;     for (int j = 0; j < 4; ++j) { const int r = 8 * j + rr; const f32x4 a = *(const LAS f32x4*)(gL + r * 64 + cg * 8), b = *(const LAS f32x4*)(gL + r * 64 + cg * 8 + 4);
;         float x[8] = {a[0], a[1], a[2], a[3], b[0], b[1], b[2], b[3]};
;         const float mean = sum8(((x[0] + x[1]) + (x[2] + x[3])) + ((x[4] + x[5]) + (x[6] + x[7]))) * (1.f / 64.f);
;         float q = 0.f;
; #pragma unroll
;         for (int i = 0; i < 8; ++i) { x[i] -= mean; q += x[i] * x[i]; }
;         const float rstd = rsqrtf(sum8(q) * (1.f / 64.f) + EPS);
; #pragma unroll
;         for (int i = 0; i < 8; ++i) { const float yy = x[i] * rstd * gg[i] + bb[i]; x[i] = yy * sigm(yy); }
;         *(v4u*)(ob + r * DP) = pack8(x); }
	v_mov_b32_e32 v26, v18
	s_waitcnt lgkmcnt(0)
	v_mov_b32_e32 v27, v22
	v_mov_b32_e32 v28, v19
	v_mov_b32_e32 v29, v23
	v_pk_add_f32 v[26:27], v[26:27], v[28:29]
	v_mov_b32_e32 v28, v20
	v_mov_b32_e32 v29, v24
	v_mov_b32_e32 v30, v21
	v_mov_b32_e32 v31, v25
	v_pk_add_f32 v[28:29], v[28:29], v[30:31]
	s_nop 0
	v_pk_add_f32 v[26:27], v[26:27], v[28:29]
	s_nop 0
	v_add_f32_e32 v26, v26, v27
	s_nop 1
	v_add_f32_dpp v26, v26, v26 quad_perm:[1,0,3,2] row_mask:0xf bank_mask:0xf bound_ctrl:1
	s_nop 1
	v_add_f32_dpp v26, v26, v26 quad_perm:[2,3,0,1] row_mask:0xf bank_mask:0xf bound_ctrl:1
	s_nop 1
	v_add_f32_dpp v26, v26, v26 row_half_mirror row_mask:0xf bank_mask:0xf bound_ctrl:1
	v_mul_f32_e32 v26, 0x3c800000, v26
	v_pk_add_f32 v[18:19], v[18:19], v[26:27] op_sel_hi:[1,0] neg_lo:[0,1] neg_hi:[0,1]
	v_pk_add_f32 v[20:21], v[20:21], v[26:27] op_sel_hi:[1,0] neg_lo:[0,1] neg_hi:[0,1]
	v_pk_mul_f32 v[28:29], v[18:19], v[18:19]
	v_pk_mul_f32 v[30:31], v[20:21], v[20:21]
	v_add_f32_e32 v28, v28, v29
	v_pk_add_f32 v[22:23], v[22:23], v[26:27] op_sel_hi:[1,0] neg_lo:[0,1] neg_hi:[0,1]
	v_add_f32_e32 v28, v30, v28
	v_pk_mul_f32 v[32:33], v[22:23], v[22:23]
	v_add_f32_e32 v28, v31, v28
	v_pk_add_f32 v[24:25], v[24:25], v[26:27] op_sel_hi:[1,0] neg_lo:[0,1] neg_hi:[0,1]
	v_add_f32_e32 v28, v32, v28
	v_pk_mul_f32 v[26:27], v[24:25], v[24:25]
	v_add_f32_e32 v28, v33, v28
	v_add_f32_e32 v26, v26, v28
	v_add_f32_e32 v26, v27, v26
	s_nop 1
	v_add_f32_dpp v26, v26, v26 quad_perm:[1,0,3,2] row_mask:0xf bank_mask:0xf bound_ctrl:1
	s_nop 1
	v_add_f32_dpp v26, v26, v26 quad_perm:[2,3,0,1] row_mask:0xf bank_mask:0xf bound_ctrl:1
	s_nop 1
	v_add_f32_dpp v26, v26, v26 row_half_mirror row_mask:0xf bank_mask:0xf bound_ctrl:1
	v_fmamk_f32 v26, v26, 0x3c800000, v168
	v_cmp_gt_f32_e32 vcc, s79, v26
	v_mul_f32_e32 v27, 0x4b800000, v26
	s_nop 0
	v_cndmask_b32_e32 v26, v26, v27, vcc
	v_rsq_f32_e32 v26, v26
	s_nop 0
	v_mul_f32_e32 v27, 0x45800000, v26
	v_cndmask_b32_e32 v26, v26, v27, vcc
	v_mul_f32_e32 v18, v18, v26
	v_fma_f32 v8, v12, v18, v8
	v_mul_f32_e32 v12, 0xbfb8aa3b, v8
	v_exp_f32_e32 v12, v12
	s_nop 0
	v_add_f32_e32 v12, 1.0, v12
	v_rcp_f32_e32 v12, v12
	s_nop 0
	v_mul_f32_e32 v8, v8, v12
	v_mul_f32_e32 v12, v19, v26
	v_fma_f32 v9, v13, v12, v9
	v_mul_f32_e32 v12, 0xbfb8aa3b, v9
	v_exp_f32_e32 v12, v12
	s_nop 0
	v_add_f32_e32 v12, 1.0, v12
	v_rcp_f32_e32 v12, v12
	s_nop 0
	v_mul_f32_e32 v9, v9, v12
	v_mul_f32_e32 v12, v20, v26
	v_fma_f32 v10, v14, v12, v10
	v_mul_f32_e32 v12, 0xbfb8aa3b, v10
	v_exp_f32_e32 v12, v12
	s_nop 0
	v_add_f32_e32 v12, 1.0, v12
	v_rcp_f32_e32 v12, v12
	s_nop 0
	v_mul_f32_e32 v10, v10, v12
	v_mul_f32_e32 v12, v21, v26
	v_fmac_f32_e32 v11, v15, v12
	v_mul_f32_e32 v12, 0xbfb8aa3b, v11
	v_exp_f32_e32 v12, v12
	s_nop 0
	v_add_f32_e32 v12, 1.0, v12
	v_rcp_f32_e32 v12, v12
	s_nop 0
	v_mul_f32_e32 v11, v11, v12
	v_mul_f32_e32 v12, v22, v26
	v_fma_f32 v0, v4, v12, v0
	v_mul_f32_e32 v4, 0xbfb8aa3b, v0
	v_exp_f32_e32 v4, v4
	s_nop 0
	v_add_f32_e32 v4, 1.0, v4
	v_rcp_f32_e32 v4, v4
	s_nop 0
	v_mul_f32_e32 v4, v0, v4
	v_mul_f32_e32 v0, v23, v26
	v_fma_f32 v0, v5, v0, v1
	v_mul_f32_e32 v1, 0xbfb8aa3b, v0
	v_exp_f32_e32 v1, v1
	s_nop 0
	v_add_f32_e32 v1, 1.0, v1
	v_rcp_f32_e32 v1, v1
	s_nop 0
	v_mul_f32_e32 v5, v0, v1
	v_mul_f32_e32 v0, v24, v26
	v_fma_f32 v0, v6, v0, v2
	v_mul_f32_e32 v1, 0xbfb8aa3b, v0
	v_exp_f32_e32 v1, v1
	s_nop 0
	v_add_f32_e32 v1, 1.0, v1
	v_rcp_f32_e32 v1, v1
	s_nop 0
	v_mul_f32_e32 v6, v0, v1
	v_mul_f32_e32 v0, v25, v26
	v_fmac_f32_e32 v3, v7, v0
	v_mul_f32_e32 v0, 0xbfb8aa3b, v3
	v_exp_f32_e32 v0, v0
	s_nop 0
	v_add_f32_e32 v0, 1.0, v0
	v_rcp_f32_e32 v0, v0
	s_nop 0
	v_mul_f32_e32 v3, v3, v0
	v_cvt_pk_bf16_f32 v0, v8, v9
	v_cvt_pk_bf16_f32 v1, v10, v11
	v_cvt_pk_bf16_f32 v2, v4, v5
	v_lshlrev_b32_e32 v4, 10, v81
	v_ashrrev_i32_e32 v5, 31, v4
	v_lshl_add_u64 v[4:5], v[4:5], 1, v[16:17]
	v_cvt_pk_bf16_f32 v3, v6, v3
	global_store_dwordx4 v[4:5], v[0:3], off
	s_waitcnt lgkmcnt(0)
